# GLA cum scans: all 8 LDS reads of each scan cluster batched before one wait (pass1 and pass3)
# baseline (speedup 1.0000x reference)
.LBB0_595:
	s_mul_hi_i32 s0, s8, 0x3e0f83e1
	s_lshr_b32 s1, s0, 31
	s_ashr_i32 s0, s0, 5
	s_add_i32 s0, s0, s1
	s_mul_i32 s1, s0, 0x84
	s_sub_i32 s20, s8, s1
	s_and_b32 s19, s0, 1
	s_bfe_u32 s21, s0, 0x20001
	s_lshl_b32 s1, s20, 6
	s_cmp_lt_i32 s20, 4
	s_cselect_b32 s9, s7, s6
	v_mov_b32_e32 v16, v207
	s_add_i32 s9, s9, s1
	v_mov_b32_e32 v10, v207
	s_cmp_eq_u32 s19, 0
	s_barrier
	s_cselect_b64 s[42:43], -1, 0
	v_ashrrev_i32_e32 v4, 3, v10
	v_lshlrev_b32_e32 v0, 4, v10
	s_cmp_eq_u32 s19, 1
	v_and_b32_e32 v2, 0x70, v0
	v_add_u32_e32 v3, s9, v4
	v_mov_b64_e32 v[0:1], s[36:37]
	s_cselect_b64 s[2:3], -1, 0
	s_and_b32 s22, s0, -8
	v_mad_i64_i32 v[0:1], s[0:1], v3, s14, v[0:1]
	s_lshl_b32 s26, s21, 8
	s_lshl_b32 s18, s21, 7
	v_lshl_add_u64 v[0:1], v[0:1], 0, s[26:27]
	v_lshlrev_b32_e32 v128, 1, v2
	v_lshlrev_b32_e32 v3, 9, v4
	v_lshlrev_b32_e32 v5, 2, v2
	v_lshl_add_u64 v[0:1], v[0:1], 0, v[128:129]
	s_mov_b64 s[0:1], -1
	s_movk_i32 s100, 0xe00
	s_cmp_eq_u32 s22, 8
	s_cselect_b32 s100, 0x400, s100
	s_lshl_b32 s101, s21, 7
	s_add_i32 s100, s100, s101
	s_lshl_b32 s100, s100, 1
	s_mov_b32 s101, 0
	v_and_b32_e32 v162, 63, v207
	v_or_b32_e32 v162, s9, v162
	v_mul_u32_u24_e32 v162, 0x1200, v162
	v_mov_b32_e32 v163, 0
	v_lshl_add_u64 v[162:163], v[162:163], 1, s[36:37]
	v_lshl_add_u64 v[162:163], v[162:163], 0, s[100:101]
	v_ashrrev_i32_e32 v164, 2, v207
	v_and_b32_e32 v164, -16, v164
	v_mov_b32_e32 v165, 0
	v_lshl_add_u64 v[162:163], v[164:165], 1, v[162:163]
	global_load_dwordx4 v[154:157], v[162:163], off
	global_load_dwordx4 v[158:161], v[162:163], off offset:16
	s_cmp_lg_u32 s22, 8
	v_add3_u32 v5, 0, v3, v5
	s_cbranch_scc0 .LBB0_613
	s_and_b64 s[0:1], s[42:43], exec
	s_cselect_b32 s26, s15, 0x1800
	v_lshl_add_u64 v[12:13], v[0:1], 0, s[26:27]
	global_load_dwordx4 v[6:9], v[12:13], off
	global_load_dwordx4 v[26:29], v[12:13], off offset:16
	v_or_b32_e32 v2, s18, v2
	v_lshlrev_b32_e32 v128, 2, v2
	v_lshl_add_u64 v[2:3], s[78:79], 0, v[128:129]
	s_waitcnt vmcnt(0) lgkmcnt(0)
	v_lshlrev_b32_e32 v11, 16, v6
	v_and_b32_e32 v25, 0xffff0000, v6
	global_load_dword v6, v[2:3], off
	v_lshlrev_b32_e32 v15, 16, v8
	v_and_b32_e32 v12, 0xffff0000, v8
	v_mul_f32_e32 v8, 0xbfb8aa3b, v11
	v_exp_f32_e32 v8, v8
	v_lshlrev_b32_e32 v20, 16, v9
	v_and_b32_e32 v17, 0xffff0000, v9
	v_lshlrev_b32_e32 v24, 16, v26
	v_add_f32_e32 v8, 1.0, v8
	v_rcp_f32_e32 v11, v8
	v_and_b32_e32 v21, 0xffff0000, v26
	v_lshlrev_b32_e32 v23, 16, v27
	v_and_b32_e32 v22, 0xffff0000, v27
	v_lshlrev_b32_e32 v19, 16, v28
	v_and_b32_e32 v18, 0xffff0000, v28
	v_mul_f32_e32 v8, 1.0, v11
	v_mul_f32_e32 v9, 0xbfb8aa3b, v25
	v_exp_f32_e32 v9, v9
	v_lshlrev_b32_e32 v30, 16, v7
	v_and_b32_e32 v31, 0xffff0000, v7
	v_lshlrev_b32_e32 v14, 16, v29
	v_add_f32_e32 v9, 1.0, v9
	v_rcp_f32_e32 v25, v9
	v_and_b32_e32 v13, 0xffff0000, v29
	v_mul_f32_e32 v15, 0xbfb8aa3b, v15
	v_exp_f32_e32 v15, v15
	v_mul_f32_e32 v9, 1.0, v25
	v_mul_f32_e32 v11, 0xbfb8aa3b, v30
	v_exp_f32_e32 v11, v11
	v_add_f32_e32 v15, 1.0, v15
	v_mul_f32_e32 v12, 0xbfb8aa3b, v12
	v_exp_f32_e32 v12, v12
	v_add_f32_e32 v11, 1.0, v11
	v_mul_f32_e32 v20, 0xbfb8aa3b, v20
	v_exp_f32_e32 v20, v20
	v_add_f32_e32 v12, 1.0, v12
	v_mul_f32_e32 v17, 0xbfb8aa3b, v17
	v_exp_f32_e32 v17, v17
	v_add_f32_e32 v20, 1.0, v20
	v_mul_f32_e32 v24, 0xbfb8aa3b, v24
	v_exp_f32_e32 v24, v24
	v_add_f32_e32 v17, 1.0, v17
	v_mul_f32_e32 v21, 0xbfb8aa3b, v21
	v_exp_f32_e32 v21, v21
	v_add_f32_e32 v24, 1.0, v24
	v_mul_f32_e32 v23, 0xbfb8aa3b, v23
	v_exp_f32_e32 v23, v23
	v_add_f32_e32 v21, 1.0, v21
	v_mul_f32_e32 v22, 0xbfb8aa3b, v22
	v_exp_f32_e32 v22, v22
	v_add_f32_e32 v23, 1.0, v23
	v_mul_f32_e32 v19, 0xbfb8aa3b, v19
	v_exp_f32_e32 v19, v19
	v_add_f32_e32 v22, 1.0, v22
	v_mul_f32_e32 v18, 0xbfb8aa3b, v18
	v_exp_f32_e32 v18, v18
	v_add_f32_e32 v19, 1.0, v19
	v_mul_f32_e32 v14, 0xbfb8aa3b, v14
	s_waitcnt vmcnt(0) lgkmcnt(0)
	v_sub_f32_e32 v7, 1.0, v6
	v_fmac_f32_e32 v6, v7, v8
	v_cmp_gt_f32_e32 vcc, s12, v6
	v_add_f32_e32 v18, 1.0, v18
	v_exp_f32_e32 v14, v14
	v_cndmask_b32_e64 v7, 0, 32, vcc
	v_ldexp_f32 v7, v6, v7
	v_log_f32_e32 v7, v7
	v_add_f32_e32 v14, 1.0, v14
	v_mul_f32_e32 v13, 0xbfb8aa3b, v13
	v_exp_f32_e32 v13, v13
	v_mul_f32_e32 v8, 0x3f317217, v7
	v_fma_f32 v8, v7, s86, -v8
	v_fmac_f32_e32 v8, 0x3377d1cf, v7
	v_fmac_f32_e32 v8, 0x3f317217, v7
	v_cmp_lt_f32_e64 s[0:1], |v7|, s87
	v_add_f32_e32 v13, 1.0, v13
	s_nop 0
	v_cndmask_b32_e64 v7, v7, v8, s[0:1]
	v_cndmask_b32_e32 v8, 0, v231, vcc
	v_sub_f32_e32 v7, v7, v8
	ds_write_b32 v5, v7
	global_load_dword v7, v[2:3], off offset:4
	s_waitcnt vmcnt(0) lgkmcnt(0)
	v_sub_f32_e32 v8, 1.0, v7
	v_fmac_f32_e32 v7, v8, v9
	v_cmp_gt_f32_e32 vcc, s12, v7
	s_nop 1
	v_cndmask_b32_e64 v8, 0, 32, vcc
	v_ldexp_f32 v8, v7, v8
	v_log_f32_e32 v8, v8
	s_nop 0
	v_mul_f32_e32 v9, 0x3f317217, v8
	v_fma_f32 v9, v8, s86, -v9
	v_fmac_f32_e32 v9, 0x3377d1cf, v8
	v_fmac_f32_e32 v9, 0x3f317217, v8
	v_cmp_lt_f32_e64 s[0:1], |v8|, s87
	s_nop 1
	v_cndmask_b32_e64 v8, v8, v9, s[0:1]
	v_cndmask_b32_e32 v9, 0, v231, vcc
	v_sub_f32_e32 v8, v8, v9
	ds_write_b32 v5, v8 offset:4
	global_load_dword v8, v[2:3], off offset:8
	v_rcp_f32_e32 v26, v11
	s_waitcnt vmcnt(0) lgkmcnt(0)
	v_sub_f32_e32 v9, 1.0, v8
	v_mul_f32_e32 v11, 1.0, v26
	v_mul_f32_e32 v25, 0xbfb8aa3b, v31
	v_exp_f32_e32 v25, v25
	v_fmac_f32_e32 v8, v11, v9
	v_add_f32_e32 v25, 1.0, v25
	v_rcp_f32_e32 v27, v25
	s_nop 0
	v_cmp_gt_f32_e32 vcc, s12, v8
	v_mul_f32_e32 v25, 1.0, v27
	s_nop 0
	v_cndmask_b32_e64 v9, 0, 32, vcc
	v_ldexp_f32 v9, v8, v9
	v_log_f32_e32 v9, v9
	s_nop 0
	v_mul_f32_e32 v11, 0x3f317217, v9
	v_fma_f32 v11, v9, s86, -v11
	v_fmac_f32_e32 v11, 0x3377d1cf, v9
	v_fmac_f32_e32 v11, 0x3f317217, v9
	v_cmp_lt_f32_e64 s[0:1], |v9|, s87
	s_nop 1
	v_cndmask_b32_e64 v9, v9, v11, s[0:1]
	v_cndmask_b32_e32 v11, 0, v231, vcc
	v_sub_f32_e32 v9, v9, v11
	ds_write_b32 v5, v9 offset:8
	global_load_dword v9, v[2:3], off offset:12
	s_waitcnt vmcnt(0) lgkmcnt(0)
	v_sub_f32_e32 v11, 1.0, v9
	v_fmac_f32_e32 v9, v25, v11
	v_cmp_gt_f32_e32 vcc, s12, v9
	s_nop 1
	v_cndmask_b32_e64 v11, 0, 32, vcc
	v_ldexp_f32 v11, v9, v11
	v_log_f32_e32 v11, v11
	s_nop 0
	v_mul_f32_e32 v25, 0x3f317217, v11
	v_fma_f32 v25, v11, s86, -v25
	v_fmac_f32_e32 v25, 0x3377d1cf, v11
	v_fmac_f32_e32 v25, 0x3f317217, v11
	v_cmp_lt_f32_e64 s[0:1], |v11|, s87
	s_nop 1
	v_cndmask_b32_e64 v11, v11, v25, s[0:1]
	v_cndmask_b32_e32 v25, 0, v231, vcc
	v_sub_f32_e32 v11, v11, v25
	ds_write_b32 v5, v11 offset:12
	global_load_dword v11, v[2:3], off offset:16
	v_rcp_f32_e32 v27, v15
	s_waitcnt vmcnt(0) lgkmcnt(0)
	v_sub_f32_e32 v25, 1.0, v11
	v_mul_f32_e32 v15, 1.0, v27
	v_rcp_f32_e32 v27, v12
	v_fmac_f32_e32 v11, v15, v25
	v_cmp_gt_f32_e32 vcc, s12, v11
	v_mul_f32_e32 v26, 1.0, v27
	s_nop 0
	v_cndmask_b32_e64 v12, 0, 32, vcc
	v_ldexp_f32 v12, v11, v12
	v_log_f32_e32 v12, v12
	s_nop 0
	v_mul_f32_e32 v15, 0x3f317217, v12
	v_fma_f32 v15, v12, s86, -v15
	v_fmac_f32_e32 v15, 0x3377d1cf, v12
	v_fmac_f32_e32 v15, 0x3f317217, v12
	v_cmp_lt_f32_e64 s[0:1], |v12|, s87
	s_nop 1
	v_cndmask_b32_e64 v12, v12, v15, s[0:1]
	v_cndmask_b32_e32 v15, 0, v231, vcc
	v_sub_f32_e32 v12, v12, v15
	ds_write_b32 v5, v12 offset:16
	global_load_dword v12, v[2:3], off offset:20
	s_waitcnt vmcnt(0) lgkmcnt(0)
	v_sub_f32_e32 v15, 1.0, v12
	v_fmac_f32_e32 v12, v26, v15
	v_cmp_gt_f32_e32 vcc, s12, v12
	s_nop 1
	v_cndmask_b32_e64 v15, 0, 32, vcc
	v_ldexp_f32 v15, v12, v15
	v_log_f32_e32 v15, v15
	s_nop 0
	v_mul_f32_e32 v25, 0x3f317217, v15
	v_fma_f32 v25, v15, s86, -v25
	v_fmac_f32_e32 v25, 0x3377d1cf, v15
	v_fmac_f32_e32 v25, 0x3f317217, v15
	v_cmp_lt_f32_e64 s[0:1], |v15|, s87
	s_nop 1
	v_cndmask_b32_e64 v15, v15, v25, s[0:1]
	v_cndmask_b32_e32 v25, 0, v231, vcc
	v_sub_f32_e32 v15, v15, v25
	ds_write_b32 v5, v15 offset:20
	global_load_dword v15, v[2:3], off offset:24
	v_rcp_f32_e32 v27, v20
	s_waitcnt vmcnt(0) lgkmcnt(0)
	v_sub_f32_e32 v25, 1.0, v15
	v_mul_f32_e32 v20, 1.0, v27
	v_rcp_f32_e32 v27, v17
	v_fmac_f32_e32 v15, v20, v25
	v_cmp_gt_f32_e32 vcc, s12, v15
	v_mul_f32_e32 v26, 1.0, v27
	s_nop 0
	v_cndmask_b32_e64 v17, 0, 32, vcc
	v_ldexp_f32 v17, v15, v17
	v_log_f32_e32 v17, v17
	s_nop 0
	v_mul_f32_e32 v20, 0x3f317217, v17
	v_fma_f32 v20, v17, s86, -v20
	v_fmac_f32_e32 v20, 0x3377d1cf, v17
	v_fmac_f32_e32 v20, 0x3f317217, v17
	v_cmp_lt_f32_e64 s[0:1], |v17|, s87
	s_nop 1
	v_cndmask_b32_e64 v17, v17, v20, s[0:1]
	v_cndmask_b32_e32 v20, 0, v231, vcc
	v_sub_f32_e32 v17, v17, v20
	ds_write_b32 v5, v17 offset:24
	global_load_dword v17, v[2:3], off offset:28
	s_waitcnt vmcnt(0) lgkmcnt(0)
	v_sub_f32_e32 v20, 1.0, v17
	v_fmac_f32_e32 v17, v26, v20
	v_cmp_gt_f32_e32 vcc, s12, v17
	s_nop 1
	v_cndmask_b32_e64 v20, 0, 32, vcc
	v_ldexp_f32 v20, v17, v20
	v_log_f32_e32 v20, v20
	s_nop 0
	v_mul_f32_e32 v25, 0x3f317217, v20
	v_fma_f32 v25, v20, s86, -v25
	v_fmac_f32_e32 v25, 0x3377d1cf, v20
	v_fmac_f32_e32 v25, 0x3f317217, v20
	v_cmp_lt_f32_e64 s[0:1], |v20|, s87
	s_nop 1
	v_cndmask_b32_e64 v20, v20, v25, s[0:1]
	v_cndmask_b32_e32 v25, 0, v231, vcc
	v_sub_f32_e32 v20, v20, v25
	ds_write_b32 v5, v20 offset:28
	global_load_dword v20, v[2:3], off offset:32
	v_rcp_f32_e32 v27, v24
	s_waitcnt vmcnt(0) lgkmcnt(0)
	v_sub_f32_e32 v25, 1.0, v20
	v_mul_f32_e32 v24, 1.0, v27
	v_rcp_f32_e32 v27, v21
	v_fmac_f32_e32 v20, v24, v25
	v_cmp_gt_f32_e32 vcc, s12, v20
	v_mul_f32_e32 v26, 1.0, v27
	s_nop 0
	v_cndmask_b32_e64 v21, 0, 32, vcc
	v_ldexp_f32 v21, v20, v21
	v_log_f32_e32 v21, v21
	s_nop 0
	v_mul_f32_e32 v24, 0x3f317217, v21
	v_fma_f32 v24, v21, s86, -v24
	v_fmac_f32_e32 v24, 0x3377d1cf, v21
	v_fmac_f32_e32 v24, 0x3f317217, v21
	v_cmp_lt_f32_e64 s[0:1], |v21|, s87
	s_nop 1
	v_cndmask_b32_e64 v21, v21, v24, s[0:1]
	v_cndmask_b32_e32 v24, 0, v231, vcc
	v_sub_f32_e32 v21, v21, v24
	ds_write_b32 v5, v21 offset:32
	global_load_dword v21, v[2:3], off offset:36
	s_waitcnt vmcnt(0) lgkmcnt(0)
	v_sub_f32_e32 v24, 1.0, v21
	v_fmac_f32_e32 v21, v26, v24
	v_cmp_gt_f32_e32 vcc, s12, v21
	s_nop 1
	v_cndmask_b32_e64 v24, 0, 32, vcc
	v_ldexp_f32 v24, v21, v24
	v_log_f32_e32 v24, v24
	s_nop 0
	v_mul_f32_e32 v25, 0x3f317217, v24
	v_fma_f32 v25, v24, s86, -v25
	v_fmac_f32_e32 v25, 0x3377d1cf, v24
	v_fmac_f32_e32 v25, 0x3f317217, v24
	v_cmp_lt_f32_e64 s[0:1], |v24|, s87
	s_nop 1
	v_cndmask_b32_e64 v24, v24, v25, s[0:1]
	v_cndmask_b32_e32 v25, 0, v231, vcc
	v_sub_f32_e32 v24, v24, v25
	ds_write_b32 v5, v24 offset:36
	global_load_dword v24, v[2:3], off offset:40
	v_rcp_f32_e32 v27, v23
	s_waitcnt vmcnt(0) lgkmcnt(0)
	v_sub_f32_e32 v25, 1.0, v24
	v_mul_f32_e32 v23, 1.0, v27
	v_rcp_f32_e32 v27, v22
	v_fmac_f32_e32 v24, v23, v25
	v_cmp_gt_f32_e32 vcc, s12, v24
	v_mul_f32_e32 v26, 1.0, v27
	s_nop 0
	v_cndmask_b32_e64 v22, 0, 32, vcc
	v_ldexp_f32 v22, v24, v22
	v_log_f32_e32 v22, v22
	s_nop 0
	v_mul_f32_e32 v23, 0x3f317217, v22
	v_fma_f32 v23, v22, s86, -v23
	v_fmac_f32_e32 v23, 0x3377d1cf, v22
	v_fmac_f32_e32 v23, 0x3f317217, v22
	v_cmp_lt_f32_e64 s[0:1], |v22|, s87
	s_nop 1
	v_cndmask_b32_e64 v22, v22, v23, s[0:1]
	v_cndmask_b32_e32 v23, 0, v231, vcc
	v_sub_f32_e32 v22, v22, v23
	ds_write_b32 v5, v22 offset:40
	global_load_dword v22, v[2:3], off offset:44
	s_waitcnt vmcnt(0) lgkmcnt(0)
	v_sub_f32_e32 v23, 1.0, v22
	v_fmac_f32_e32 v22, v26, v23
	v_cmp_gt_f32_e32 vcc, s12, v22
	s_nop 1
	v_cndmask_b32_e64 v23, 0, 32, vcc
	v_ldexp_f32 v23, v22, v23
	v_log_f32_e32 v23, v23
	s_nop 0
	v_mul_f32_e32 v25, 0x3f317217, v23
	v_fma_f32 v25, v23, s86, -v25
	v_fmac_f32_e32 v25, 0x3377d1cf, v23
	v_fmac_f32_e32 v25, 0x3f317217, v23
	v_cmp_lt_f32_e64 s[0:1], |v23|, s87
	s_nop 1
	v_cndmask_b32_e64 v23, v23, v25, s[0:1]
	v_cndmask_b32_e32 v25, 0, v231, vcc
	v_sub_f32_e32 v23, v23, v25
	ds_write_b32 v5, v23 offset:44
	global_load_dword v23, v[2:3], off offset:48
	v_rcp_f32_e32 v27, v19
	s_waitcnt vmcnt(0) lgkmcnt(0)
	v_sub_f32_e32 v25, 1.0, v23
	v_mul_f32_e32 v19, 1.0, v27
	v_rcp_f32_e32 v27, v18
	v_fmac_f32_e32 v23, v19, v25
	v_cmp_gt_f32_e32 vcc, s12, v23
	v_mul_f32_e32 v26, 1.0, v27
	s_nop 0
	v_cndmask_b32_e64 v18, 0, 32, vcc
	v_ldexp_f32 v18, v23, v18
	v_log_f32_e32 v18, v18
	s_nop 0
	v_mul_f32_e32 v19, 0x3f317217, v18
	v_fma_f32 v19, v18, s86, -v19
	v_fmac_f32_e32 v19, 0x3377d1cf, v18
	v_fmac_f32_e32 v19, 0x3f317217, v18
	v_cmp_lt_f32_e64 s[0:1], |v18|, s87
	s_nop 1
	v_cndmask_b32_e64 v18, v18, v19, s[0:1]
	v_cndmask_b32_e32 v19, 0, v231, vcc
	v_sub_f32_e32 v18, v18, v19
	ds_write_b32 v5, v18 offset:48
	global_load_dword v18, v[2:3], off offset:52
	s_waitcnt vmcnt(0) lgkmcnt(0)
	v_sub_f32_e32 v19, 1.0, v18
	v_fmac_f32_e32 v18, v26, v19
	v_cmp_gt_f32_e32 vcc, s12, v18
	s_nop 1
	v_cndmask_b32_e64 v19, 0, 32, vcc
	v_ldexp_f32 v19, v18, v19
	v_log_f32_e32 v19, v19
	s_nop 0
	v_mul_f32_e32 v25, 0x3f317217, v19
	v_fma_f32 v25, v19, s86, -v25
	v_fmac_f32_e32 v25, 0x3377d1cf, v19
	v_fmac_f32_e32 v25, 0x3f317217, v19
	v_cmp_lt_f32_e64 s[0:1], |v19|, s87
	s_nop 1
	v_cndmask_b32_e64 v19, v19, v25, s[0:1]
	v_cndmask_b32_e32 v25, 0, v231, vcc
	v_sub_f32_e32 v19, v19, v25
	ds_write_b32 v5, v19 offset:52
	global_load_dword v25, v[2:3], off offset:56
	v_rcp_f32_e32 v27, v14
	s_waitcnt vmcnt(0) lgkmcnt(0)
	v_sub_f32_e32 v19, 1.0, v25
	v_mul_f32_e32 v14, 1.0, v27
	v_rcp_f32_e32 v27, v13
	v_fmac_f32_e32 v25, v14, v19
	v_cmp_gt_f32_e32 vcc, s12, v25
	v_mul_f32_e32 v13, 1.0, v27
	s_nop 0
	v_cndmask_b32_e64 v14, 0, 32, vcc
	v_ldexp_f32 v14, v25, v14
	v_log_f32_e32 v14, v14
	s_nop 0
	v_mul_f32_e32 v19, 0x3f317217, v14
	v_fma_f32 v19, v14, s86, -v19
	v_fmac_f32_e32 v19, 0x3377d1cf, v14
	v_fmac_f32_e32 v19, 0x3f317217, v14
	v_cmp_lt_f32_e64 s[0:1], |v14|, s87
	s_nop 1
	v_cndmask_b32_e64 v14, v14, v19, s[0:1]
	v_cndmask_b32_e32 v19, 0, v231, vcc
	v_sub_f32_e32 v14, v14, v19
	ds_write_b32 v5, v14 offset:56
	global_load_dword v3, v[2:3], off offset:60
	s_waitcnt vmcnt(0) lgkmcnt(0)
	v_sub_f32_e32 v2, 1.0, v3
	v_fmac_f32_e32 v3, v13, v2
	v_cmp_gt_f32_e32 vcc, s12, v3
	s_nop 1
	v_cndmask_b32_e64 v2, 0, 32, vcc
	v_ldexp_f32 v2, v3, v2
	v_log_f32_e32 v2, v2
	s_nop 0
	v_mul_f32_e32 v13, 0x3f317217, v2
	v_fma_f32 v13, v2, s86, -v13
	v_fmac_f32_e32 v13, 0x3377d1cf, v2
	v_fmac_f32_e32 v13, 0x3f317217, v2
	v_cmp_lt_f32_e64 s[0:1], |v2|, s87
	s_nop 1
	v_cndmask_b32_e64 v2, v2, v13, s[0:1]
	v_cndmask_b32_e32 v13, 0, v231, vcc
	v_sub_f32_e32 v2, v2, v13
	v_ashrrev_i32_e32 v13, 7, v10
	v_and_b32_e32 v10, 0x7f, v10
	v_lshlrev_b32_e32 v14, 13, v13
	v_lshlrev_b32_e32 v19, 2, v10
	ds_write_b32 v5, v2 offset:60
	v_add3_u32 v2, 0, v19, v14
	s_mov_b64 s[0:1], -1
	s_and_b64 vcc, exec, s[2:3]
	s_waitcnt lgkmcnt(0)
	s_barrier
	s_cbranch_vccz .LBB0_598
	ds_read2st64_b32 v[166:167], v2 offset0:28 offset1:30
	ds_read2st64_b32 v[168:169], v2 offset0:24 offset1:26
	ds_read2st64_b32 v[170:171], v2 offset0:20 offset1:22
	ds_read2st64_b32 v[172:173], v2 offset0:16 offset1:18
	ds_read2st64_b32 v[174:175], v2 offset0:12 offset1:14
	ds_read2st64_b32 v[176:177], v2 offset0:8 offset1:10
	ds_read2st64_b32 v[178:179], v2 offset0:4 offset1:6
	ds_read2st64_b32 v[180:181], v2 offset1:2
	s_mov_b64 s[0:1], 0
	s_waitcnt lgkmcnt(0)
	v_add_f32_e32 v27, 0, v167
	v_add_f32_e32 v28, v27, v166
	ds_write2st64_b32 v2, v28, v27 offset0:28 offset1:30
	v_add_f32_e32 v27, v28, v169
	v_add_f32_e32 v28, v27, v168
	ds_write2st64_b32 v2, v28, v27 offset0:24 offset1:26
	v_add_f32_e32 v27, v28, v171
	v_add_f32_e32 v28, v27, v170
	ds_write2st64_b32 v2, v28, v27 offset0:20 offset1:22
	v_add_f32_e32 v27, v28, v173
	v_add_f32_e32 v28, v27, v172
	ds_write2st64_b32 v2, v28, v27 offset0:16 offset1:18
	v_add_f32_e32 v27, v28, v175
	v_add_f32_e32 v28, v27, v174
	ds_write2st64_b32 v2, v28, v27 offset0:12 offset1:14
	v_add_f32_e32 v27, v28, v177
	v_add_f32_e32 v28, v27, v176
	ds_write2st64_b32 v2, v28, v27 offset0:8 offset1:10
	v_add_f32_e32 v27, v28, v179
	v_add_f32_e32 v28, v27, v178
	ds_write2st64_b32 v2, v28, v27 offset0:4 offset1:6
	v_add_f32_e32 v27, v28, v181
	v_add_f32_e32 v26, v27, v180
	ds_write2st64_b32 v2, v26, v27 offset1:2
.LBB0_598:
	s_andn2_b64 vcc, exec, s[0:1]
	s_cbranch_vccnz .LBB0_600
	ds_read2st64_b32 v[166:167], v2 offset1:2
	ds_read2st64_b32 v[168:169], v2 offset0:4 offset1:6
	ds_read2st64_b32 v[170:171], v2 offset0:8 offset1:10
	ds_read2st64_b32 v[172:173], v2 offset0:12 offset1:14
	ds_read2st64_b32 v[174:175], v2 offset0:16 offset1:18
	ds_read2st64_b32 v[176:177], v2 offset0:20 offset1:22
	ds_read2st64_b32 v[178:179], v2 offset0:24 offset1:26
	ds_read2st64_b32 v[180:181], v2 offset0:28 offset1:30
	s_waitcnt lgkmcnt(0)
	v_add_f32_e32 v26, 0, v166
	v_add_f32_e32 v28, v26, v167
	ds_write2st64_b32 v2, v26, v28 offset1:2
	v_add_f32_e32 v26, v28, v168
	v_add_f32_e32 v28, v26, v169
	ds_write2st64_b32 v2, v26, v28 offset0:4 offset1:6
	v_add_f32_e32 v26, v28, v170
	v_add_f32_e32 v28, v26, v171
	ds_write2st64_b32 v2, v26, v28 offset0:8 offset1:10
	v_add_f32_e32 v26, v28, v172
	v_add_f32_e32 v28, v26, v173
	ds_write2st64_b32 v2, v26, v28 offset0:12 offset1:14
	v_add_f32_e32 v26, v28, v174
	v_add_f32_e32 v28, v26, v175
	ds_write2st64_b32 v2, v26, v28 offset0:16 offset1:18
	v_add_f32_e32 v26, v28, v176
	v_add_f32_e32 v28, v26, v177
	ds_write2st64_b32 v2, v26, v28 offset0:20 offset1:22
	v_add_f32_e32 v26, v28, v178
	v_add_f32_e32 v28, v26, v179
	ds_write2st64_b32 v2, v26, v28 offset0:24 offset1:26
	v_add_f32_e32 v26, v28, v180
	v_add_f32_e32 v27, v26, v181
	ds_write2st64_b32 v2, v26, v27 offset0:28 offset1:30

.LBB0_612:
	v_sub_f32_e32 v35, 1.0, v6
	v_sub_f32_e32 v34, 1.0, v7
	s_barrier
	ds_read2st64_b32 v[166:167], v2 offset1:2
	ds_read2st64_b32 v[168:169], v2 offset0:4 offset1:6
	ds_read2st64_b32 v[170:171], v2 offset0:8 offset1:10
	ds_read2st64_b32 v[172:173], v2 offset0:12 offset1:14
	ds_read2st64_b32 v[174:175], v2 offset0:16 offset1:18
	ds_read2st64_b32 v[176:177], v2 offset0:20 offset1:22
	ds_read2st64_b32 v[178:179], v2 offset0:24 offset1:26
	ds_read2st64_b32 v[180:181], v2 offset0:28 offset1:30
	v_sub_f32_e32 v28, 1.0, v17
	v_sub_f32_e32 v17, 1.0, v3
	v_sub_f32_e32 v33, 1.0, v8
	v_sub_f32_e32 v32, 1.0, v9
	s_waitcnt lgkmcnt(0)
	v_add_f32_e32 v3, v36, v166
	v_add_f32_e32 v6, v36, v167
	ds_write2st64_b32 v2, v3, v6 offset1:2
	v_sub_f32_e32 v31, 1.0, v11
	v_sub_f32_e32 v30, 1.0, v12
	v_sub_f32_e32 v29, 1.0, v15
	v_sub_f32_e32 v27, 1.0, v20
	v_add_f32_e32 v3, v36, v168
	v_add_f32_e32 v6, v36, v169
	ds_write2st64_b32 v2, v3, v6 offset0:4 offset1:6
	v_sub_f32_e32 v26, 1.0, v21
	v_sub_f32_e32 v24, 1.0, v24
	v_sub_f32_e32 v21, 1.0, v22
	v_sub_f32_e32 v20, 1.0, v23
	v_add_f32_e32 v3, v36, v170
	v_add_f32_e32 v6, v36, v171
	ds_write2st64_b32 v2, v3, v6 offset0:8 offset1:10
	v_sub_f32_e32 v19, 1.0, v18
	v_sub_f32_e32 v18, 1.0, v25
	s_mov_b64 s[0:1], 0
	v_add_f32_e32 v3, v36, v172
	v_add_f32_e32 v6, v36, v173
	ds_write2st64_b32 v2, v3, v6 offset0:12 offset1:14
	v_add_f32_e32 v3, v36, v174
	v_add_f32_e32 v6, v36, v175
	ds_write2st64_b32 v2, v3, v6 offset0:16 offset1:18
	v_add_f32_e32 v3, v36, v176
	v_add_f32_e32 v6, v36, v177
	ds_write2st64_b32 v2, v3, v6 offset0:20 offset1:22
	v_add_f32_e32 v3, v36, v178
	v_add_f32_e32 v6, v36, v179
	ds_write2st64_b32 v2, v3, v6 offset0:24 offset1:26
	v_add_f32_e32 v3, v36, v180
	v_add_f32_e32 v6, v36, v181
	ds_write2st64_b32 v2, v3, v6 offset0:28 offset1:30
	s_waitcnt lgkmcnt(0)
	s_barrier

.LBB0_736:
	s_xor_b64 s[18:19], s[92:93], -1
	s_or_b32 s0, s95, s23
	s_mul_hi_i32 s8, s0, 0x84
	s_mul_i32 s9, s0, 0x84
	s_and_b64 s[0:1], s[92:93], exec
	s_cselect_b32 s0, s21, s94
	s_ashr_i32 s1, s0, 31
	s_add_u32 s0, s9, s0
	s_addc_u32 s1, s8, s1
	s_lshl_b64 s[0:1], s[0:1], 15
	v_lshl_add_u64 v[16:17], v[86:87], 0, s[0:1]
	global_load_dwordx4 v[60:63], v[16:17], off
	global_load_dwordx4 v[56:59], v[16:17], off offset:32
	global_load_dwordx4 v[52:55], v[16:17], off offset:64
	global_load_dwordx4 v[48:51], v[16:17], off offset:96
	global_load_dwordx4 v[44:47], v[16:17], off offset:128
	global_load_dwordx4 v[40:43], v[16:17], off offset:160
	global_load_dwordx4 v[36:39], v[16:17], off offset:192
	global_load_dwordx4 v[32:35], v[16:17], off offset:224
	v_mov_b32_e32 v113, v207
	s_and_b64 vcc, exec, s[96:97]
	v_ashrrev_i32_e32 v110, 3, v113
	v_lshlrev_b32_e32 v16, 4, v113
	v_and_b32_e32 v111, 0x70, v16
	v_add_u32_e32 v18, s22, v110
	v_mov_b64_e32 v[16:17], s[2:3]
	v_mad_i64_i32 v[16:17], s[0:1], v18, s14, v[16:17]
	v_lshlrev_b32_e32 v128, 1, v111
	v_lshl_add_u64 v[90:91], v[16:17], 0, v[128:129]
	v_lshlrev_b32_e32 v16, 9, v110
	v_lshlrev_b32_e32 v17, 2, v111
	v_add3_u32 v109, 0, v16, v17
	s_mov_b64 s[0:1], -1
	s_cbranch_vccz .LBB0_754
	s_and_b64 s[0:1], s[92:93], exec
	s_cselect_b32 s26, s15, 0x1800
	v_lshl_add_u64 v[20:21], v[90:91], 0, s[26:27]
	global_load_dwordx4 v[16:19], v[20:21], off
	global_load_dwordx4 v[116:119], v[20:21], off offset:16
	s_waitcnt vmcnt(0) lgkmcnt(0)
	v_lshlrev_b32_e32 v20, 16, v16
	v_and_b32_e32 v112, 0xffff0000, v16
	v_or_b32_e32 v16, s20, v111
	v_lshlrev_b32_e32 v128, 2, v16
	v_lshlrev_b32_e32 v115, 16, v17
	v_and_b32_e32 v120, 0xffff0000, v17
	v_lshl_add_u64 v[16:17], s[78:79], 0, v[128:129]
	global_load_dword v111, v[16:17], off
	v_lshlrev_b32_e32 v31, 16, v19
	v_and_b32_e32 v30, 0xffff0000, v19
	v_mul_f32_e32 v19, 0xbfb8aa3b, v20
	v_exp_f32_e32 v19, v19
	v_lshlrev_b32_e32 v29, 16, v116
	v_and_b32_e32 v28, 0xffff0000, v116
	v_lshlrev_b32_e32 v27, 16, v117
	v_add_f32_e32 v19, 1.0, v19
	v_rcp_f32_e32 v116, v19
	v_and_b32_e32 v26, 0xffff0000, v117
	v_lshlrev_b32_e32 v25, 16, v118
	v_and_b32_e32 v24, 0xffff0000, v118
	v_lshlrev_b32_e32 v23, 16, v119
	v_and_b32_e32 v22, 0xffff0000, v119
	v_mul_f32_e32 v19, 1.0, v116
	v_mul_f32_e32 v20, 0xbfb8aa3b, v112
	v_exp_f32_e32 v20, v20
	v_lshlrev_b32_e32 v114, 16, v18
	v_and_b32_e32 v21, 0xffff0000, v18
	v_mul_f32_e32 v114, 0xbfb8aa3b, v114
	v_add_f32_e32 v20, 1.0, v20
	v_rcp_f32_e32 v116, v20
	v_exp_f32_e32 v114, v114
	v_mul_f32_e32 v21, 0xbfb8aa3b, v21
	v_exp_f32_e32 v21, v21
	v_mul_f32_e32 v20, 1.0, v116
	v_add_f32_e32 v114, 1.0, v114
	v_add_f32_e32 v21, 1.0, v21
	v_mul_f32_e32 v31, 0xbfb8aa3b, v31
	v_exp_f32_e32 v31, v31
	v_mul_f32_e32 v30, 0xbfb8aa3b, v30
	v_exp_f32_e32 v30, v30
	v_mul_f32_e32 v29, 0xbfb8aa3b, v29
	v_add_f32_e32 v31, 1.0, v31
	v_exp_f32_e32 v29, v29
	v_add_f32_e32 v30, 1.0, v30
	v_mul_f32_e32 v28, 0xbfb8aa3b, v28
	v_exp_f32_e32 v28, v28
	v_add_f32_e32 v29, 1.0, v29
	v_mul_f32_e32 v27, 0xbfb8aa3b, v27
	v_exp_f32_e32 v27, v27
	v_add_f32_e32 v28, 1.0, v28
	v_mul_f32_e32 v26, 0xbfb8aa3b, v26
	v_exp_f32_e32 v26, v26
	v_add_f32_e32 v27, 1.0, v27
	v_mul_f32_e32 v25, 0xbfb8aa3b, v25
	v_exp_f32_e32 v25, v25
	v_add_f32_e32 v26, 1.0, v26
	v_mul_f32_e32 v24, 0xbfb8aa3b, v24
	v_exp_f32_e32 v24, v24
	v_add_f32_e32 v25, 1.0, v25
	v_mul_f32_e32 v23, 0xbfb8aa3b, v23
	v_exp_f32_e32 v23, v23
	v_add_f32_e32 v24, 1.0, v24
	v_mul_f32_e32 v22, 0xbfb8aa3b, v22
	v_exp_f32_e32 v22, v22
	v_add_f32_e32 v23, 1.0, v23
	s_waitcnt vmcnt(0) lgkmcnt(0)
	v_sub_f32_e32 v18, 1.0, v111
	v_fmac_f32_e32 v111, v18, v19
	v_cmp_gt_f32_e32 vcc, s12, v111
	v_add_f32_e32 v22, 1.0, v22
	s_nop 0
	v_cndmask_b32_e64 v18, 0, 32, vcc
	v_ldexp_f32 v18, v111, v18
	v_log_f32_e32 v18, v18
	s_nop 0
	v_mul_f32_e32 v19, 0x3f317217, v18
	v_fma_f32 v19, v18, s86, -v19
	v_fmac_f32_e32 v19, 0x3377d1cf, v18
	v_fmac_f32_e32 v19, 0x3f317217, v18
	v_cmp_lt_f32_e64 s[0:1], |v18|, s87
	s_nop 1
	v_cndmask_b32_e64 v18, v18, v19, s[0:1]
	v_cndmask_b32_e32 v19, 0, v231, vcc
	v_sub_f32_e32 v18, v18, v19
	ds_write_b32 v109, v18
	global_load_dword v112, v[16:17], off offset:4
	s_waitcnt vmcnt(0) lgkmcnt(0)
	v_sub_f32_e32 v18, 1.0, v112
	v_fmac_f32_e32 v112, v18, v20
	v_cmp_gt_f32_e32 vcc, s12, v112
	v_mul_f32_e32 v20, 0xbfb8aa3b, v115
	v_exp_f32_e32 v20, v20
	v_cndmask_b32_e64 v18, 0, 32, vcc
	v_ldexp_f32 v18, v112, v18
	v_log_f32_e32 v18, v18
	v_add_f32_e32 v20, 1.0, v20
	v_mul_f32_e32 v19, 0x3f317217, v18
	v_fma_f32 v19, v18, s86, -v19
	v_fmac_f32_e32 v19, 0x3377d1cf, v18
	v_fmac_f32_e32 v19, 0x3f317217, v18
	v_cmp_lt_f32_e64 s[0:1], |v18|, s87
	s_nop 1
	v_cndmask_b32_e64 v18, v18, v19, s[0:1]
	v_cndmask_b32_e32 v19, 0, v231, vcc
	v_sub_f32_e32 v18, v18, v19
	ds_write_b32 v109, v18 offset:4
	global_load_dword v18, v[16:17], off offset:8
	v_rcp_f32_e32 v116, v20
	s_waitcnt vmcnt(0) lgkmcnt(0)
	v_sub_f32_e32 v19, 1.0, v18
	v_mul_f32_e32 v20, 1.0, v116
	v_mul_f32_e32 v115, 0xbfb8aa3b, v120
	v_exp_f32_e32 v115, v115
	v_fmac_f32_e32 v18, v20, v19
	v_add_f32_e32 v115, 1.0, v115
	v_rcp_f32_e32 v117, v115
	s_nop 0
	v_cmp_gt_f32_e32 vcc, s12, v18
	v_mul_f32_e32 v115, 1.0, v117
	s_nop 0
	v_cndmask_b32_e64 v19, 0, 32, vcc
	v_ldexp_f32 v19, v18, v19
	v_log_f32_e32 v19, v19
	s_nop 0
	v_mul_f32_e32 v20, 0x3f317217, v19
	v_fma_f32 v20, v19, s86, -v20
	v_fmac_f32_e32 v20, 0x3377d1cf, v19
	v_fmac_f32_e32 v20, 0x3f317217, v19
	v_cmp_lt_f32_e64 s[0:1], |v19|, s87
	s_nop 1
	v_cndmask_b32_e64 v19, v19, v20, s[0:1]
	v_cndmask_b32_e32 v20, 0, v231, vcc
	v_sub_f32_e32 v19, v19, v20
	ds_write_b32 v109, v19 offset:8
	global_load_dword v19, v[16:17], off offset:12
	s_waitcnt vmcnt(0) lgkmcnt(0)
	v_sub_f32_e32 v20, 1.0, v19
	v_fmac_f32_e32 v19, v115, v20
	v_cmp_gt_f32_e32 vcc, s12, v19
	s_nop 1
	v_cndmask_b32_e64 v20, 0, 32, vcc
	v_ldexp_f32 v20, v19, v20
	v_log_f32_e32 v20, v20
	s_nop 0
	v_mul_f32_e32 v115, 0x3f317217, v20
	v_fma_f32 v115, v20, s86, -v115
	v_fmac_f32_e32 v115, 0x3377d1cf, v20
	v_fmac_f32_e32 v115, 0x3f317217, v20
	v_cmp_lt_f32_e64 s[0:1], |v20|, s87
	s_nop 1
	v_cndmask_b32_e64 v20, v20, v115, s[0:1]
	v_cndmask_b32_e32 v115, 0, v231, vcc
	v_sub_f32_e32 v20, v20, v115
	ds_write_b32 v109, v20 offset:12
	global_load_dword v20, v[16:17], off offset:16
	v_rcp_f32_e32 v117, v114
	s_waitcnt vmcnt(0) lgkmcnt(0)
	v_sub_f32_e32 v115, 1.0, v20
	v_mul_f32_e32 v114, 1.0, v117
	v_rcp_f32_e32 v117, v21
	v_fmac_f32_e32 v20, v114, v115
	v_cmp_gt_f32_e32 vcc, s12, v20
	v_mul_f32_e32 v116, 1.0, v117
	s_nop 0
	v_cndmask_b32_e64 v21, 0, 32, vcc
	v_ldexp_f32 v21, v20, v21
	v_log_f32_e32 v21, v21
	s_nop 0
	v_mul_f32_e32 v114, 0x3f317217, v21
	v_fma_f32 v114, v21, s86, -v114
	v_fmac_f32_e32 v114, 0x3377d1cf, v21
	v_fmac_f32_e32 v114, 0x3f317217, v21
	v_cmp_lt_f32_e64 s[0:1], |v21|, s87
	s_nop 1
	v_cndmask_b32_e64 v21, v21, v114, s[0:1]
	v_cndmask_b32_e32 v114, 0, v231, vcc
	v_sub_f32_e32 v21, v21, v114
	ds_write_b32 v109, v21 offset:16
	global_load_dword v21, v[16:17], off offset:20
	s_waitcnt vmcnt(0) lgkmcnt(0)
	v_sub_f32_e32 v114, 1.0, v21
	v_fmac_f32_e32 v21, v116, v114
	v_cmp_gt_f32_e32 vcc, s12, v21
	s_nop 1
	v_cndmask_b32_e64 v114, 0, 32, vcc
	v_ldexp_f32 v114, v21, v114
	v_log_f32_e32 v114, v114
	s_nop 0
	v_mul_f32_e32 v115, 0x3f317217, v114
	v_fma_f32 v115, v114, s86, -v115
	v_fmac_f32_e32 v115, 0x3377d1cf, v114
	v_fmac_f32_e32 v115, 0x3f317217, v114
	v_cmp_lt_f32_e64 s[0:1], |v114|, s87
	s_nop 1
	v_cndmask_b32_e64 v114, v114, v115, s[0:1]
	v_cndmask_b32_e32 v115, 0, v231, vcc
	v_sub_f32_e32 v114, v114, v115
	ds_write_b32 v109, v114 offset:20
	global_load_dword v114, v[16:17], off offset:24
	v_rcp_f32_e32 v117, v31
	s_waitcnt vmcnt(0) lgkmcnt(0)
	v_sub_f32_e32 v115, 1.0, v114
	v_mul_f32_e32 v31, 1.0, v117
	v_rcp_f32_e32 v117, v30
	v_fmac_f32_e32 v114, v31, v115
	v_cmp_gt_f32_e32 vcc, s12, v114
	v_mul_f32_e32 v30, 1.0, v117
	s_nop 0
	v_cndmask_b32_e64 v31, 0, 32, vcc
	v_ldexp_f32 v31, v114, v31
	v_log_f32_e32 v31, v31
	s_nop 0
	v_mul_f32_e32 v115, 0x3f317217, v31
	v_fma_f32 v115, v31, s86, -v115
	v_fmac_f32_e32 v115, 0x3377d1cf, v31
	v_fmac_f32_e32 v115, 0x3f317217, v31
	v_cmp_lt_f32_e64 s[0:1], |v31|, s87
	s_nop 1
	v_cndmask_b32_e64 v31, v31, v115, s[0:1]
	v_cndmask_b32_e32 v115, 0, v231, vcc
	v_sub_f32_e32 v31, v31, v115
	ds_write_b32 v109, v31 offset:24
	global_load_dword v115, v[16:17], off offset:28
	s_waitcnt vmcnt(0) lgkmcnt(0)
	v_sub_f32_e32 v31, 1.0, v115
	v_fmac_f32_e32 v115, v30, v31
	v_cmp_gt_f32_e32 vcc, s12, v115
	s_nop 1
	v_cndmask_b32_e64 v30, 0, 32, vcc
	v_ldexp_f32 v30, v115, v30
	v_log_f32_e32 v30, v30
	s_nop 0
	v_mul_f32_e32 v31, 0x3f317217, v30
	v_fma_f32 v31, v30, s86, -v31
	v_fmac_f32_e32 v31, 0x3377d1cf, v30
	v_fmac_f32_e32 v31, 0x3f317217, v30
	v_cmp_lt_f32_e64 s[0:1], |v30|, s87
	s_nop 1
	v_cndmask_b32_e64 v30, v30, v31, s[0:1]
	v_cndmask_b32_e32 v31, 0, v231, vcc
	v_sub_f32_e32 v30, v30, v31
	ds_write_b32 v109, v30 offset:28
	global_load_dword v116, v[16:17], off offset:32
	v_rcp_f32_e32 v117, v29
	s_waitcnt vmcnt(0) lgkmcnt(0)
	v_sub_f32_e32 v30, 1.0, v116
	v_mul_f32_e32 v29, 1.0, v117
	v_rcp_f32_e32 v117, v28
	v_fmac_f32_e32 v116, v29, v30
	v_cmp_gt_f32_e32 vcc, s12, v116
	v_mul_f32_e32 v28, 1.0, v117
	s_nop 0
	v_cndmask_b32_e64 v29, 0, 32, vcc
	v_ldexp_f32 v29, v116, v29
	v_log_f32_e32 v29, v29
	s_nop 0
	v_mul_f32_e32 v30, 0x3f317217, v29
	v_fma_f32 v30, v29, s86, -v30
	v_fmac_f32_e32 v30, 0x3377d1cf, v29
	v_fmac_f32_e32 v30, 0x3f317217, v29
	v_cmp_lt_f32_e64 s[0:1], |v29|, s87
	s_nop 1
	v_cndmask_b32_e64 v29, v29, v30, s[0:1]
	v_cndmask_b32_e32 v30, 0, v231, vcc
	v_sub_f32_e32 v29, v29, v30
	ds_write_b32 v109, v29 offset:32
	global_load_dword v117, v[16:17], off offset:36
	s_waitcnt vmcnt(0) lgkmcnt(0)
	v_sub_f32_e32 v29, 1.0, v117
	v_fmac_f32_e32 v117, v28, v29
	v_cmp_gt_f32_e32 vcc, s12, v117
	s_nop 1
	v_cndmask_b32_e64 v28, 0, 32, vcc
	v_ldexp_f32 v28, v117, v28
	v_log_f32_e32 v28, v28
	s_nop 0
	v_mul_f32_e32 v29, 0x3f317217, v28
	v_fma_f32 v29, v28, s86, -v29
	v_fmac_f32_e32 v29, 0x3377d1cf, v28
	v_fmac_f32_e32 v29, 0x3f317217, v28
	v_cmp_lt_f32_e64 s[0:1], |v28|, s87
	s_nop 1
	v_cndmask_b32_e64 v28, v28, v29, s[0:1]
	v_cndmask_b32_e32 v29, 0, v231, vcc
	v_sub_f32_e32 v28, v28, v29
	ds_write_b32 v109, v28 offset:36
	global_load_dword v118, v[16:17], off offset:40
	v_rcp_f32_e32 v30, v27
	s_waitcnt vmcnt(0) lgkmcnt(0)
	v_sub_f32_e32 v28, 1.0, v118
	v_mul_f32_e32 v27, 1.0, v30
	v_rcp_f32_e32 v30, v26
	v_fmac_f32_e32 v118, v27, v28
	v_cmp_gt_f32_e32 vcc, s12, v118
	v_mul_f32_e32 v29, 1.0, v30
	s_nop 0
	v_cndmask_b32_e64 v26, 0, 32, vcc
	v_ldexp_f32 v26, v118, v26
	v_log_f32_e32 v26, v26
	s_nop 0
	v_mul_f32_e32 v27, 0x3f317217, v26
	v_fma_f32 v27, v26, s86, -v27
	v_fmac_f32_e32 v27, 0x3377d1cf, v26
	v_fmac_f32_e32 v27, 0x3f317217, v26
	v_cmp_lt_f32_e64 s[0:1], |v26|, s87
	s_nop 1
	v_cndmask_b32_e64 v26, v26, v27, s[0:1]
	v_cndmask_b32_e32 v27, 0, v231, vcc
	v_sub_f32_e32 v26, v26, v27
	ds_write_b32 v109, v26 offset:40
	global_load_dword v26, v[16:17], off offset:44
	s_waitcnt vmcnt(0) lgkmcnt(0)
	v_sub_f32_e32 v27, 1.0, v26
	v_fmac_f32_e32 v26, v29, v27
	v_cmp_gt_f32_e32 vcc, s12, v26
	s_nop 1
	v_cndmask_b32_e64 v27, 0, 32, vcc
	v_ldexp_f32 v27, v26, v27
	v_log_f32_e32 v27, v27
	s_nop 0
	v_mul_f32_e32 v28, 0x3f317217, v27
	v_fma_f32 v28, v27, s86, -v28
	v_fmac_f32_e32 v28, 0x3377d1cf, v27
	v_fmac_f32_e32 v28, 0x3f317217, v27
	v_cmp_lt_f32_e64 s[0:1], |v27|, s87
	s_nop 1
	v_cndmask_b32_e64 v27, v27, v28, s[0:1]
	v_cndmask_b32_e32 v28, 0, v231, vcc
	v_sub_f32_e32 v27, v27, v28
	ds_write_b32 v109, v27 offset:44
	global_load_dword v27, v[16:17], off offset:48
	v_rcp_f32_e32 v30, v25
	s_waitcnt vmcnt(0) lgkmcnt(0)
	v_sub_f32_e32 v28, 1.0, v27
	v_mul_f32_e32 v25, 1.0, v30
	v_rcp_f32_e32 v30, v24
	v_fmac_f32_e32 v27, v25, v28
	v_cmp_gt_f32_e32 vcc, s12, v27
	v_mul_f32_e32 v29, 1.0, v30
	s_nop 0
	v_cndmask_b32_e64 v24, 0, 32, vcc
	v_ldexp_f32 v24, v27, v24
	v_log_f32_e32 v24, v24
	s_nop 0
	v_mul_f32_e32 v25, 0x3f317217, v24
	v_fma_f32 v25, v24, s86, -v25
	v_fmac_f32_e32 v25, 0x3377d1cf, v24
	v_fmac_f32_e32 v25, 0x3f317217, v24
	v_cmp_lt_f32_e64 s[0:1], |v24|, s87
	s_nop 1
	v_cndmask_b32_e64 v24, v24, v25, s[0:1]
	v_cndmask_b32_e32 v25, 0, v231, vcc
	v_sub_f32_e32 v24, v24, v25
	ds_write_b32 v109, v24 offset:48
	global_load_dword v24, v[16:17], off offset:52
	s_waitcnt vmcnt(0) lgkmcnt(0)
	v_sub_f32_e32 v25, 1.0, v24
	v_fmac_f32_e32 v24, v29, v25
	v_cmp_gt_f32_e32 vcc, s12, v24
	s_nop 1
	v_cndmask_b32_e64 v25, 0, 32, vcc
	v_ldexp_f32 v25, v24, v25
	v_log_f32_e32 v25, v25
	s_nop 0
	v_mul_f32_e32 v28, 0x3f317217, v25
	v_fma_f32 v28, v25, s86, -v28
	v_fmac_f32_e32 v28, 0x3377d1cf, v25
	v_fmac_f32_e32 v28, 0x3f317217, v25
	v_cmp_lt_f32_e64 s[0:1], |v25|, s87
	s_nop 1
	v_cndmask_b32_e64 v25, v25, v28, s[0:1]
	v_cndmask_b32_e32 v28, 0, v231, vcc
	v_sub_f32_e32 v25, v25, v28
	ds_write_b32 v109, v25 offset:52
	global_load_dword v25, v[16:17], off offset:56
	v_rcp_f32_e32 v30, v23
	s_waitcnt vmcnt(0) lgkmcnt(0)
	v_sub_f32_e32 v28, 1.0, v25
	v_mul_f32_e32 v23, 1.0, v30
	v_rcp_f32_e32 v30, v22
	v_fmac_f32_e32 v25, v23, v28
	v_cmp_gt_f32_e32 vcc, s12, v25
	v_mul_f32_e32 v22, 1.0, v30
	s_nop 0
	v_cndmask_b32_e64 v23, 0, 32, vcc
	v_ldexp_f32 v23, v25, v23
	v_log_f32_e32 v23, v23
	s_nop 0
	v_mul_f32_e32 v28, 0x3f317217, v23
	v_fma_f32 v28, v23, s86, -v28
	v_fmac_f32_e32 v28, 0x3377d1cf, v23
	v_fmac_f32_e32 v28, 0x3f317217, v23
	v_cmp_lt_f32_e64 s[0:1], |v23|, s87
	s_nop 1
	v_cndmask_b32_e64 v23, v23, v28, s[0:1]
	v_cndmask_b32_e32 v28, 0, v231, vcc
	v_sub_f32_e32 v23, v23, v28
	ds_write_b32 v109, v23 offset:56
	global_load_dword v16, v[16:17], off offset:60
	s_waitcnt vmcnt(0) lgkmcnt(0)
	v_sub_f32_e32 v17, 1.0, v16
	v_fmac_f32_e32 v16, v22, v17
	v_cmp_gt_f32_e32 vcc, s12, v16
	s_nop 1
	v_cndmask_b32_e64 v17, 0, 32, vcc
	v_ldexp_f32 v17, v16, v17
	v_log_f32_e32 v17, v17
	s_nop 0
	v_mul_f32_e32 v22, 0x3f317217, v17
	v_fma_f32 v22, v17, s86, -v22
	v_fmac_f32_e32 v22, 0x3377d1cf, v17
	v_fmac_f32_e32 v22, 0x3f317217, v17
	v_cmp_lt_f32_e64 s[0:1], |v17|, s87
	s_nop 1
	v_cndmask_b32_e64 v17, v17, v22, s[0:1]
	v_cndmask_b32_e32 v22, 0, v231, vcc
	v_sub_f32_e32 v17, v17, v22
	ds_write_b32 v109, v17 offset:60
	v_ashrrev_i32_e32 v17, 7, v113
	v_and_b32_e32 v22, 0x7f, v113
	v_lshlrev_b32_e32 v23, 13, v17
	v_lshlrev_b32_e32 v28, 2, v22
	v_add3_u32 v113, 0, v28, v23
	s_mov_b64 s[0:1], -1
	s_and_b64 vcc, exec, s[18:19]
	s_waitcnt lgkmcnt(0)
	s_barrier
	s_cbranch_vccz .LBB0_739
	ds_read2st64_b32 v[166:167], v113 offset0:28 offset1:30
	ds_read2st64_b32 v[168:169], v113 offset0:24 offset1:26
	ds_read2st64_b32 v[170:171], v113 offset0:20 offset1:22
	ds_read2st64_b32 v[172:173], v113 offset0:16 offset1:18
	ds_read2st64_b32 v[174:175], v113 offset0:12 offset1:14
	ds_read2st64_b32 v[176:177], v113 offset0:8 offset1:10
	ds_read2st64_b32 v[178:179], v113 offset0:4 offset1:6
	ds_read2st64_b32 v[180:181], v113 offset1:2
	s_mov_b64 s[0:1], 0
	s_waitcnt lgkmcnt(0)
	v_add_f32_e32 v29, 0, v167
	v_add_f32_e32 v119, v29, v166
	ds_write2st64_b32 v113, v119, v29 offset0:28 offset1:30
	v_add_f32_e32 v29, v119, v169
	v_add_f32_e32 v119, v29, v168
	ds_write2st64_b32 v113, v119, v29 offset0:24 offset1:26
	v_add_f32_e32 v29, v119, v171
	v_add_f32_e32 v119, v29, v170
	ds_write2st64_b32 v113, v119, v29 offset0:20 offset1:22
	v_add_f32_e32 v29, v119, v173
	v_add_f32_e32 v119, v29, v172
	ds_write2st64_b32 v113, v119, v29 offset0:16 offset1:18
	v_add_f32_e32 v29, v119, v175
	v_add_f32_e32 v119, v29, v174
	ds_write2st64_b32 v113, v119, v29 offset0:12 offset1:14
	v_add_f32_e32 v29, v119, v177
	v_add_f32_e32 v119, v29, v176
	ds_write2st64_b32 v113, v119, v29 offset0:8 offset1:10
	v_add_f32_e32 v29, v119, v179
	v_add_f32_e32 v119, v29, v178
	ds_write2st64_b32 v113, v119, v29 offset0:4 offset1:6
	v_add_f32_e32 v29, v119, v181
	v_add_f32_e32 v30, v29, v180
	ds_write2st64_b32 v113, v30, v29 offset1:2
.LBB0_739:
	s_andn2_b64 vcc, exec, s[0:1]
	s_cbranch_vccnz .LBB0_741
	ds_read2st64_b32 v[166:167], v113 offset1:2
	ds_read2st64_b32 v[168:169], v113 offset0:4 offset1:6
	ds_read2st64_b32 v[170:171], v113 offset0:8 offset1:10
	ds_read2st64_b32 v[172:173], v113 offset0:12 offset1:14
	ds_read2st64_b32 v[174:175], v113 offset0:16 offset1:18
	ds_read2st64_b32 v[176:177], v113 offset0:20 offset1:22
	ds_read2st64_b32 v[178:179], v113 offset0:24 offset1:26
	ds_read2st64_b32 v[180:181], v113 offset0:28 offset1:30
	s_waitcnt lgkmcnt(0)
	v_add_f32_e32 v29, 0, v166
	v_add_f32_e32 v119, v29, v167
	ds_write2st64_b32 v113, v29, v119 offset1:2
	v_add_f32_e32 v29, v119, v168
	v_add_f32_e32 v119, v29, v169
	ds_write2st64_b32 v113, v29, v119 offset0:4 offset1:6
	v_add_f32_e32 v29, v119, v170
	v_add_f32_e32 v119, v29, v171
	ds_write2st64_b32 v113, v29, v119 offset0:8 offset1:10
	v_add_f32_e32 v29, v119, v172
	v_add_f32_e32 v119, v29, v173
	ds_write2st64_b32 v113, v29, v119 offset0:12 offset1:14
	v_add_f32_e32 v29, v119, v174
	v_add_f32_e32 v119, v29, v175
	ds_write2st64_b32 v113, v29, v119 offset0:16 offset1:18
	v_add_f32_e32 v29, v119, v176
	v_add_f32_e32 v119, v29, v177
	ds_write2st64_b32 v113, v29, v119 offset0:20 offset1:22
	v_add_f32_e32 v29, v119, v178
	v_add_f32_e32 v119, v29, v179
	ds_write2st64_b32 v113, v29, v119 offset0:24 offset1:26
	v_add_f32_e32 v29, v119, v180
	v_add_f32_e32 v30, v29, v181
	ds_write2st64_b32 v113, v29, v30 offset0:28 offset1:30

.LBB0_753:
	v_sub_f32_e32 v23, 1.0, v115
	v_sub_f32_e32 v22, 1.0, v114
	s_barrier
	ds_read2st64_b32 v[166:167], v113 offset1:2
	ds_read2st64_b32 v[168:169], v113 offset0:4 offset1:6
	ds_read2st64_b32 v[170:171], v113 offset0:8 offset1:10
	ds_read2st64_b32 v[172:173], v113 offset0:12 offset1:14
	ds_read2st64_b32 v[174:175], v113 offset0:16 offset1:18
	ds_read2st64_b32 v[176:177], v113 offset0:20 offset1:22
	ds_read2st64_b32 v[178:179], v113 offset0:24 offset1:26
	ds_read2st64_b32 v[180:181], v113 offset0:28 offset1:30
	v_sub_f32_e32 v31, 1.0, v16
	v_sub_f32_e32 v17, 1.0, v112
	v_sub_f32_e32 v16, 1.0, v111
	v_sub_f32_e32 v30, 1.0, v25
	s_waitcnt lgkmcnt(0)
	v_add_f32_e32 v111, v119, v166
	v_add_f32_e32 v112, v119, v167
	ds_write2st64_b32 v113, v111, v112 offset1:2
	v_sub_f32_e32 v29, 1.0, v24
	v_sub_f32_e32 v28, 1.0, v27
	v_sub_f32_e32 v27, 1.0, v26
	v_add_f32_e32 v111, v119, v168
	v_add_f32_e32 v112, v119, v169
	ds_write2st64_b32 v113, v111, v112 offset0:4 offset1:6
	v_sub_f32_e32 v26, 1.0, v118
	v_sub_f32_e32 v25, 1.0, v117
	v_sub_f32_e32 v24, 1.0, v116
	v_add_f32_e32 v111, v119, v170
	v_add_f32_e32 v112, v119, v171
	ds_write2st64_b32 v113, v111, v112 offset0:8 offset1:10
	v_sub_f32_e32 v21, 1.0, v21
	v_sub_f32_e32 v20, 1.0, v20
	v_sub_f32_e32 v19, 1.0, v19
	v_add_f32_e32 v111, v119, v172
	v_add_f32_e32 v112, v119, v173
	ds_write2st64_b32 v113, v111, v112 offset0:12 offset1:14
	v_sub_f32_e32 v18, 1.0, v18
	s_mov_b64 s[0:1], 0
	v_add_f32_e32 v111, v119, v174
	v_add_f32_e32 v112, v119, v175
	ds_write2st64_b32 v113, v111, v112 offset0:16 offset1:18
	v_add_f32_e32 v111, v119, v176
	v_add_f32_e32 v112, v119, v177
	ds_write2st64_b32 v113, v111, v112 offset0:20 offset1:22
	v_add_f32_e32 v111, v119, v178
	v_add_f32_e32 v112, v119, v179
	ds_write2st64_b32 v113, v111, v112 offset0:24 offset1:26
	v_add_f32_e32 v111, v119, v180
	v_add_f32_e32 v112, v119, v181
	ds_write2st64_b32 v113, v111, v112 offset0:28 offset1:30
	s_waitcnt lgkmcnt(0)
	s_barrier
